# P2a sgu_prompt: the 6 later weight-row loads of the W->Wm conversion issued with the first two (one wait instead of four serialized rounds)
# baseline (speedup 1.0000x reference)
; __device__ __forceinline__ void sgu_prompt_item(int item, const u16* PROJ, u16* MIXIN, const float* gln, const float* bln, const float* wsp, const float* bsp, LAS unsigned char* lds, int& hh_cached) {
;     ...
; #pragma unroll
;     for (int i = 0; i < 4; ++i) { const int idx = tid + 512 * i, s = idx >> 4, ch = (idx & 15) * 8; rv[i] = *(const u32x4*)(PROJ + (row0 + s) * NPROJ + C_VS + hh * 128 + ch); }
;     u32x2 uw[8];
; #pragma unroll
;     for (int dct = 0; dct < 8; ++dct) uw[dct] = *(const u32x2*)(PROJ + (row0 + 16 * w + (lane & 15)) * NPROJ + C_U + hh * 128 + 16 * dct + (lane >> 4) * 4);
;     const float bs = bsp[hh * 128 + 16 * w + (lane & 15)];
;     if (hh != hh_cached) {
.LBB0_236:
	s_ashr_i32 s58, s50, 6
	s_ashr_i32 s59, s58, 31
	s_lshl_b32 s6, s50, 5
	s_lshl_b64 s[78:79], s[58:59], 11
	s_and_b32 s6, s6, 0x780
	s_or_b32 s78, s78, s6
	v_or_b32_e32 v0, s78, v32
	v_mov_b64_e32 v[16:17], s[4:5]
	s_and_b32 s56, s50, 3
	v_mad_u64_u32 v[0:1], s[58:59], v0, s30, v[16:17]
	v_mad_i32_i24 v1, s79, v154, v1
	s_lshl_b32 s6, s56, 8
	v_or_b32_e32 v2, s78, v68
	v_lshl_add_u64 v[0:1], v[0:1], 0, s[6:7]
	v_lshlrev_b32_e32 v52, 1, v60
	v_mad_u64_u32 v[2:3], s[58:59], v2, s30, v[16:17]
	v_readfirstlane_b32 s55, v129
	v_lshl_add_u64 v[0:1], v[0:1], 0, v[52:53]
	v_mad_i32_i24 v3, s79, v154, v3
	v_or_b32_e32 v8, s78, v70
	v_add_co_u32_e32 v0, vcc, s3, v0
	v_lshl_add_u64 v[2:3], v[2:3], 0, s[6:7]
	v_mad_u64_u32 v[8:9], s[58:59], v8, s30, v[16:17]
	s_lshr_b32 s54, s55, 2
	s_lshl_b32 s35, s56, 7
	v_addc_co_u32_e32 v1, vcc, 0, v1, vcc
	v_lshl_add_u64 v[2:3], v[2:3], 0, v[52:53]
	v_mad_i32_i24 v9, s79, v154, v9
	v_lshl_add_u64 v[10:11], s[78:79], 0, v[72:73]
	s_and_b32 s54, s54, 0x3ffffff0
	v_add_co_u32_e32 v4, vcc, s3, v2
	v_lshl_add_u64 v[8:9], v[8:9], 0, s[6:7]
	v_mad_u64_u32 v[12:13], s[58:59], v10, s30, v[16:17]
	s_add_u32 s57, s78, s54
	v_addc_co_u32_e32 v5, vcc, 0, v3, vcc
	v_lshl_add_u64 v[8:9], v[8:9], 0, v[52:53]
	v_mad_i32_i24 v13, v11, s30, v13
	v_or_b32_e32 v18, s57, v64
	v_add_co_u32_e32 v8, vcc, s3, v8
	v_lshl_add_u64 v[10:11], v[12:13], 0, s[6:7]
	s_addc_u32 s60, s79, 0
	v_mad_u64_u32 v[16:17], s[58:59], v18, s30, v[16:17]
	v_addc_co_u32_e32 v9, vcc, 0, v9, vcc
	v_lshl_add_u64 v[10:11], v[10:11], 0, v[52:53]
	v_mad_i32_i24 v17, s60, v154, v17
	v_add_co_u32_e32 v12, vcc, s3, v10
	v_lshl_add_u64 v[16:17], v[16:17], 0, s[6:7]
	v_lshlrev_b32_e32 v102, 1, v66
	v_mov_b32_e32 v103, v53
	v_addc_co_u32_e32 v13, vcc, 0, v11, vcc
	v_lshl_add_u64 v[16:17], v[16:17], 0, v[102:103]
	global_load_dwordx4 v[0:3], v[0:1], off offset:32
	s_nop 0
	global_load_dwordx4 v[4:7], v[4:5], off offset:32
	s_nop 0
	global_load_dwordx4 v[8:11], v[8:9], off offset:32
	s_nop 0
	global_load_dwordx4 v[12:15], v[12:13], off offset:32
	s_nop 0
	global_load_dwordx2 v[104:105], v[16:17], off offset:3104
	global_load_dwordx2 v[100:101], v[16:17], off offset:3136
	global_load_dwordx2 v[98:99], v[16:17], off offset:3168
	global_load_dwordx2 v[96:97], v[16:17], off offset:3200
	global_load_dwordx2 v[94:95], v[16:17], off offset:3232
	global_load_dwordx2 v[92:93], v[16:17], off offset:3264
	global_load_dwordx2 v[90:91], v[16:17], off offset:3296
	global_load_dwordx2 v[88:89], v[16:17], off offset:3328
	s_add_i32 s6, s54, s35
	v_or_b32_e32 v52, s6, v64
	v_lshl_add_u64 v[16:17], v[52:53], 2, s[48:49]
	global_load_dword v79, v[16:17], off
	s_cmp_eq_u32 s56, s51
	s_cbranch_scc1 .LBB0_238
; #define LAS __attribute__((address_space(3)))
; __device__ __forceinline__ unsigned pk2(float lo, float hi) { unsigned r; asm("v_cvt_pk_bf16_f32 %0, %1, %2" : "=v"(r) : "v"(lo), "v"(hi)); return r; }
; __device__ __forceinline__ void sgu_prompt_item(int item, const u16* PROJ, u16* MIXIN, const float* gln, const float* bln, const float* wsp, const float* bsp, LAS unsigned char* lds, int& hh_cached) {
;     ...
;         const int t = tid >> 2, s0 = (tid & 3) * 32; const float* wp = wsp + ((size_t)hh * 128 + t) * 128 + s0;
; #pragma unroll
;         for (int q = 0; q < 4; ++q) { const f32x4 a = *(const f32x4*)(wp + 8 * q), b = *(const f32x4*)(wp + 8 * q + 4); const int s = s0 + 8 * q;
;             u32x4 o; o.x = pk2(s <= t ? a.x : 0.f, s + 1 <= t ? a.y : 0.f); o.y = pk2(s + 2 <= t ? a.z : 0.f, s + 3 <= t ? a.w : 0.f);
;             o.z = pk2(s + 4 <= t ? b.x : 0.f, s + 5 <= t ? b.y : 0.f); o.w = pk2(s + 6 <= t ? b.z : 0.f, s + 7 <= t ? b.w : 0.f);
;             *(LAS u32x4*)(Wm + t * LD2 + s) = o; }
;         hh_cached = hh;
	s_lshl_b32 s6, s56, 14
	v_add_lshl_u32 v52, s6, v119, 2
	v_lshl_add_u64 v[16:17], v[74:75], 0, v[52:53]
	global_load_dwordx4 v[18:21], v[16:17], off offset:16
	global_load_dwordx4 v[22:25], v[16:17], off
	global_load_dwordx4 v[204:207], v[16:17], off offset:48
	global_load_dwordx4 v[208:211], v[16:17], off offset:32
	global_load_dwordx4 v[212:215], v[16:17], off offset:80
	global_load_dwordx4 v[216:219], v[16:17], off offset:64
	global_load_dwordx4 v[220:223], v[16:17], off offset:112
	global_load_dwordx4 v[224:227], v[16:17], off offset:96
	v_readlane_b32 s58, v237, 20
	v_readlane_b32 s59, v237, 21
	s_mov_b32 s51, s56
	s_waitcnt vmcnt(0)
	v_cndmask_b32_e64 v22, v22, 0, s[58:59]
	v_readlane_b32 s58, v237, 22
	v_readlane_b32 s59, v237, 23
	s_nop 1
	v_cndmask_b32_e64 v23, 0, v23, s[58:59]
	v_readlane_b32 s58, v237, 24
	v_readlane_b32 s59, v237, 25
	v_cvt_pk_bf16_f32 v22, v22, v23
	s_nop 1
	v_cndmask_b32_e64 v23, v24, 0, s[58:59]
	v_readlane_b32 s58, v237, 26
	v_readlane_b32 s59, v237, 27
	s_nop 1
	v_cndmask_b32_e64 v24, v25, 0, s[58:59]
	v_readlane_b32 s58, v237, 28
	v_readlane_b32 s59, v237, 29
	v_cvt_pk_bf16_f32 v23, v23, v24
	s_nop 1
	v_cndmask_b32_e64 v18, v18, 0, s[58:59]
	v_readlane_b32 s58, v237, 30
	v_readlane_b32 s59, v237, 31
	s_nop 1
	v_cndmask_b32_e64 v19, v19, 0, s[58:59]
	v_readlane_b32 s58, v237, 32
	v_readlane_b32 s59, v237, 33
	v_cvt_pk_bf16_f32 v24, v18, v19
	s_nop 1
	v_cndmask_b32_e64 v18, v20, 0, s[58:59]
	v_readlane_b32 s58, v237, 34
	v_readlane_b32 s59, v237, 35
	s_nop 1
	v_cndmask_b32_e64 v19, v21, 0, s[58:59]
	v_cvt_pk_bf16_f32 v25, v18, v19
	ds_write_b128 v120, v[22:25] offset:34816
	s_nop 0
	s_nop 0
	v_readlane_b32 s58, v237, 36
	v_readlane_b32 s59, v237, 37
	s_nop 0
	s_nop 0
	v_cndmask_b32_e64 v22, v208, 0, s[58:59]
	v_readlane_b32 s58, v237, 38
	v_readlane_b32 s59, v237, 39
	s_nop 1
	v_cndmask_b32_e64 v23, 0, v209, s[58:59]
	v_readlane_b32 s58, v237, 40
	v_readlane_b32 s59, v237, 41
	v_cvt_pk_bf16_f32 v22, v22, v23
	s_nop 1
	v_cndmask_b32_e64 v23, v210, 0, s[58:59]
	v_readlane_b32 s58, v237, 42
	v_readlane_b32 s59, v237, 43
	s_nop 1
	v_cndmask_b32_e64 v24, v211, 0, s[58:59]
	v_readlane_b32 s58, v237, 44
	v_readlane_b32 s59, v237, 45
	v_cvt_pk_bf16_f32 v23, v23, v24
	s_nop 1
	v_cndmask_b32_e64 v18, v204, 0, s[58:59]
	v_readlane_b32 s58, v237, 46
	v_readlane_b32 s59, v237, 47
	s_nop 1
	v_cndmask_b32_e64 v19, v205, 0, s[58:59]
	v_readlane_b32 s58, v237, 48
	v_readlane_b32 s59, v237, 49
	v_cvt_pk_bf16_f32 v24, v18, v19
	s_nop 1
	v_cndmask_b32_e64 v18, v206, 0, s[58:59]
	v_readlane_b32 s58, v237, 50
	v_readlane_b32 s59, v237, 51
	s_nop 1
	v_cndmask_b32_e64 v19, v207, 0, s[58:59]
	v_cvt_pk_bf16_f32 v25, v18, v19
	ds_write_b128 v120, v[22:25] offset:34832
	s_nop 0
	s_nop 0
	v_readlane_b32 s58, v237, 52
	v_readlane_b32 s59, v237, 53
	s_nop 0
	s_nop 0
	v_cndmask_b32_e64 v22, v216, 0, s[58:59]
	v_readlane_b32 s58, v237, 54
	v_readlane_b32 s59, v237, 55
	s_nop 1
	v_cndmask_b32_e64 v23, 0, v217, s[58:59]
	v_readlane_b32 s58, v237, 56
	v_readlane_b32 s59, v237, 57
	v_cvt_pk_bf16_f32 v22, v22, v23
	s_nop 1
	v_cndmask_b32_e64 v23, v218, 0, s[58:59]
	v_readlane_b32 s58, v237, 58
	v_readlane_b32 s59, v237, 59
	s_nop 1
	v_cndmask_b32_e64 v24, v219, 0, s[58:59]
	v_readlane_b32 s58, v237, 60
	v_readlane_b32 s59, v237, 61
	v_cvt_pk_bf16_f32 v23, v23, v24
	s_nop 1
	v_cndmask_b32_e64 v18, v212, 0, s[58:59]
	v_readlane_b32 s58, v237, 62
	v_readlane_b32 s59, v237, 63
	s_nop 1
	v_cndmask_b32_e64 v19, v213, 0, s[58:59]
	v_readlane_b32 s58, v236, 0
	v_readlane_b32 s59, v236, 1
	v_cvt_pk_bf16_f32 v24, v18, v19
	s_nop 1
	v_cndmask_b32_e64 v18, v214, 0, s[58:59]
	v_readlane_b32 s58, v236, 2
	v_readlane_b32 s59, v236, 3
	s_nop 1
	v_cndmask_b32_e64 v19, v215, 0, s[58:59]
	v_cvt_pk_bf16_f32 v25, v18, v19
	ds_write_b128 v120, v[22:25] offset:34848
	s_nop 0
	s_nop 0
	v_readlane_b32 s58, v236, 4
	v_readlane_b32 s59, v236, 5
	s_nop 0
	v_cndmask_b32_e64 v18, v220, 0, s[68:69]
	s_nop 0
	v_cndmask_b32_e64 v16, v224, 0, s[58:59]
	v_readlane_b32 s58, v236, 6
	v_readlane_b32 s59, v236, 7
	v_cndmask_b32_e64 v19, v221, 0, s[70:71]
	v_cvt_pk_bf16_f32 v18, v18, v19
	v_cndmask_b32_e64 v19, v222, 0, s[72:73]
	v_cndmask_b32_e64 v17, 0, v225, s[58:59]
	v_readlane_b32 s58, v236, 8
	v_readlane_b32 s59, v236, 9
	v_cvt_pk_bf16_f32 v16, v16, v17
	v_cndmask_b32_e64 v22, v227, 0, s[66:67]
	v_cndmask_b32_e64 v20, v223, 0, s[74:75]
	v_cndmask_b32_e64 v17, v226, 0, s[58:59]
	v_cvt_pk_bf16_f32 v17, v17, v22
	v_cvt_pk_bf16_f32 v19, v19, v20
	ds_write_b128 v120, v[16:19] offset:34864
